# embed LN (phase 0): gamma/beta loaded once before the row loop as in the other LN phases
# speedup vs baseline: 1.0039x; 1.0039x over previous
;   __device__ __forceinline__ const float* I(int i) const { return (const float*)(const GAS float*)in[i]; }
; __device__ __forceinline__ void ln_row_regs(f32x4 (&v)[4], const float* g, const float* bb, int lane) {
;     ...
;     const f32x4 gg = *(const f32x4*)(g + lane * 4 + i * 256), b4 = *(const f32x4*)(bb + lane * 4 + i * 256);
; __device__ __forceinline__ void embed_ln(const Params& p, int bid, int nb, const int tid) {
;     ...
;   f32x4 nx[4];
;   { const float* s0 = src_of(min(bid * 4 + wv, MT - 1));
; #pragma unroll
;     for (int i = 0; i < 4; ++i) nx[i] = *(const f32x4*)(s0 + lane * 4 + i * 256); }
;   for (int row = bid * 4 + wv; row < MT; row += nb * 4) {
;     f32x4 v[4];
; #pragma unroll
;     for (int i = 0; i < 4; ++i) v[i] = nx[i];
;     { const float* s1 = src_of(min(row + nb * 4, MT - 1));
; #pragma unroll
;       for (int i = 0; i < 4; ++i) nx[i] = *(const f32x4*)(s1 + lane * 4 + i * 256); }
;     ln_row_regs(v, p.I(8), p.I(9), lane);
.LBB0_671:
	s_or_b64 exec, exec, s[2:3]
	s_movk_i32 s2, 0x4280
	v_cmp_gt_i32_e32 vcc, s2, v50
	s_and_saveexec_b64 s[2:3], vcc
	s_cbranch_execz .LBB0_682
	v_lshlrev_b32_e32 v2, 2, v130
	v_and_b32_e32 v20, 0xfc, v2
	v_lshlrev_b64 v[0:1], 12, v[0:1]
	v_lshl_add_u64 v[0:1], v[4:5], 0, v[0:1]
	v_lshlrev_b32_e32 v2, 2, v20
	v_lshl_add_u64 v[0:1], v[0:1], 0, v[2:3]
	global_load_dwordx4 v[16:19], v[0:1], off
	global_load_dwordx4 v[12:15], v[0:1], off offset:1024
	global_load_dwordx4 v[8:11], v[0:1], off offset:2048
	global_load_dwordx4 v[4:7], v[0:1], off offset:3072
	v_and_b32_e32 v0, 64, v157
	v_add_u32_e32 v0, 64, v0
	v_xor_b32_e32 v1, 32, v157
	v_cmp_lt_i32_e32 vcc, v1, v0
	v_readlane_b32 s40, v254, 29
	v_ashrrev_i32_e32 v23, 31, v22
	v_cndmask_b32_e32 v1, v157, v1, vcc
	v_lshlrev_b32_e32 v51, 2, v1
	v_xor_b32_e32 v1, 16, v157
	v_cmp_lt_i32_e32 vcc, v1, v0
	s_ashr_i32 s37, s36, 31
	v_readlane_b32 s41, v254, 30
	v_cndmask_b32_e32 v1, v157, v1, vcc
	v_lshlrev_b32_e32 v52, 2, v1
	v_xor_b32_e32 v1, 8, v157
	v_cmp_lt_i32_e32 vcc, v1, v0
	v_readlane_b32 s42, v254, 31
	v_readlane_b32 s43, v254, 32
	v_cndmask_b32_e32 v1, v157, v1, vcc
	v_lshlrev_b32_e32 v53, 2, v1
	v_xor_b32_e32 v1, 4, v157
	v_cmp_lt_i32_e32 vcc, v1, v0
	v_lshl_add_u64 v[22:23], v[22:23], 0, s[36:37]
	s_waitcnt vmcnt(4)
	v_lshl_add_u64 v[38:39], s[42:43], 0, v[2:3]
	v_cndmask_b32_e32 v1, v157, v1, vcc
	v_lshlrev_b32_e32 v54, 2, v1
	v_xor_b32_e32 v1, 2, v157
	v_cmp_lt_i32_e32 vcc, v1, v0
	v_lshlrev_b64 v[24:25], 12, v[22:23]
	v_readlane_b32 s24, v254, 9
	v_cndmask_b32_e32 v1, v157, v1, vcc
	v_lshlrev_b32_e32 v55, 2, v1
	v_xor_b32_e32 v1, 1, v157
	v_cmp_lt_i32_e32 vcc, v1, v0
	v_readlane_b32 s25, v254, 10
	s_lshl_b32 s34, s0, 2
	v_cndmask_b32_e32 v0, v157, v1, vcc
	v_lshlrev_b32_e32 v56, 2, v0
	v_lshl_add_u64 v[0:1], s[40:41], 0, v[2:3]
	v_and_b32_e32 v2, 63, v130
	v_lshl_or_b32 v24, v2, 4, v24
	v_lshl_add_u64 v[40:41], s[24:25], 0, v[24:25]
	v_lshlrev_b64 v[22:23], 11, v[22:23]
	v_readlane_b32 s24, v254, 11
	s_ashr_i32 s35, s34, 31
	v_lshl_or_b32 v22, v2, 3, v22
	v_readlane_b32 s25, v254, 12
	s_lshl_b64 s[36:37], s[34:35], 12
	s_lshl_b64 s[38:39], s[34:35], 11
	v_lshl_add_u64 v[42:43], s[24:25], 0, v[22:23]
	s_mov_b64 s[40:41], 0
	v_lshlrev_b32_e32 v2, 2, v20
	v_readlane_b32 s44, v254, 33
	v_readlane_b32 s45, v254, 34
	v_readlane_b32 s46, v254, 35
	v_readlane_b32 s47, v254, 36
	s_waitcnt vmcnt(3)
	v_mov_b32_e32 v34, v17
	v_mov_b32_e32 v35, v18
	v_mov_b32_e32 v17, v19
	s_waitcnt vmcnt(2)
	v_mov_b32_e32 v36, v13
	v_mov_b32_e32 v37, v14
	v_mov_b32_e32 v13, v15
	s_waitcnt vmcnt(0)
	v_mov_b32_e32 v44, v4
	v_mov_b32_e32 v48, v5
	v_mov_b32_e32 v14, v6
	v_mov_b32_e32 v46, v7
	global_load_dwordx4 v[184:187], v[0:1], off
	global_load_dwordx4 v[188:191], v[0:1], off offset:1024
	global_load_dwordx4 v[192:195], v[0:1], off offset:2048
	global_load_dwordx4 v[196:199], v[0:1], off offset:3072
	global_load_dwordx4 v[210:213], v[38:39], off
	global_load_dwordx4 v[214:217], v[38:39], off offset:1024
	global_load_dwordx4 v[218:221], v[38:39], off offset:2048
	global_load_dwordx4 v[222:225], v[38:39], off offset:3072
	s_branch .LBB0_675

;   __device__ __forceinline__ const float* I(int i) const { return (const float*)(const GAS float*)in[i]; }
; __device__ __forceinline__ unsigned pk2(float lo, float hi) { const f32x2_t v = {lo, hi}; const bf16x2_t b = __builtin_convertvector(v, bf16x2_t); return __builtin_bit_cast(unsigned, b); }
; __device__ __forceinline__ void ln_row_regs(f32x4 (&v)[4], const float* g, const float* bb, int lane) {
;   float s = 0.f;
; #pragma unroll
;   for (int i = 0; i < 4; ++i) s += (v[i][0] + v[i][1]) + (v[i][2] + v[i][3]);
;   const float mu = wave_sum(s) * (1.0f / 1024.0f);
;   float q = 0.f;
; #pragma unroll
;   for (int i = 0; i < 4; ++i) { const f32x4 d = v[i] - mu; q += (d[0] * d[0] + d[1] * d[1]) + (d[2] * d[2] + d[3] * d[3]); }
;   const float rs = rsqrtf(wave_sum(q) * (1.0f / 1024.0f) + 1e-5f);
; #pragma unroll
;   for (int i = 0; i < 4; ++i) {
;     const f32x4 gg = *(const f32x4*)(g + lane * 4 + i * 256), b4 = *(const f32x4*)(bb + lane * 4 + i * 256);
;     v[i] = (v[i] - mu) * rs * gg + b4;
;   }
; __device__ __forceinline__ void embed_ln(const Params& p, int bid, int nb, const int tid) {
;     ...
;   for (int row = bid * 4 + wv; row < MT; row += nb * 4) {
;     f32x4 v[4];
; #pragma unroll
;     for (int i = 0; i < 4; ++i) v[i] = nx[i];
;     { const float* s1 = src_of(min(row + nb * 4, MT - 1));
; #pragma unroll
;       for (int i = 0; i < 4; ++i) nx[i] = *(const f32x4*)(s1 + lane * 4 + i * 256); }
;     ln_row_regs(v, p.I(8), p.I(9), lane);
; #pragma unroll
;     for (int i = 0; i < 4; ++i) {
;       *(f32x4*)(X + (size_t)row * 1024 + lane * 4 + i * 256) = v[i];
;       uint2 o; o.x = pk2(v[i][0], v[i][1]); o.y = pk2(v[i][2], v[i][3]);
;       *(uint2*)(Xb + (size_t)row * 1024 + lane * 4 + i * 256) = o;
;     }
;   }
.LBB0_674:
	s_or_b64 exec, exec, s[42:43]
	v_pk_add_f32 v[58:59], v[34:35], v[16:17]
	v_add_f32_e32 v45, v8, v9
	v_add_f32_e32 v15, v58, v59
	v_pk_add_f32 v[58:59], v[36:37], v[12:13]
	v_add_f32_e32 v47, 0, v15
	v_pk_add_f32 v[58:59], v[58:59], v[58:59] op_sel_hi:[0,1]
	v_add_f32_e32 v49, v10, v11
	v_mov_b32_e32 v15, v59
	v_pk_add_f32 v[44:45], v[44:45], v[48:49]
	v_pk_add_f32 v[14:15], v[14:15], v[46:47]
	v_lshlrev_b64 v[18:19], 12, v[18:19]
	v_pk_add_f32 v[14:15], v[44:45], v[14:15]
	v_lshl_add_u64 v[18:19], v[20:21], 0, v[18:19]
	v_add_f32_e32 v14, v14, v15
	ds_bpermute_b32 v15, v51, v14
	v_lshl_add_u64 v[18:19], v[18:19], 0, v[2:3]
	global_load_dwordx4 v[30:33], v[18:19], off
	global_load_dwordx4 v[26:29], v[18:19], off offset:1024
	global_load_dwordx4 v[22:25], v[18:19], off offset:2048
	s_nop 0
	global_load_dwordx4 v[18:21], v[18:19], off offset:3072
	s_waitcnt lgkmcnt(0)
	v_add_f32_e32 v14, v14, v15
	ds_bpermute_b32 v15, v52, v14
	s_waitcnt lgkmcnt(0)
	v_add_f32_e32 v14, v14, v15
	ds_bpermute_b32 v15, v53, v14
	s_waitcnt lgkmcnt(0)
	v_add_f32_e32 v14, v14, v15
	ds_bpermute_b32 v15, v54, v14
	s_waitcnt lgkmcnt(0)
	v_add_f32_e32 v14, v14, v15
	ds_bpermute_b32 v15, v55, v14
	s_waitcnt lgkmcnt(0)
	v_add_f32_e32 v14, v14, v15
	ds_bpermute_b32 v15, v56, v14
	s_waitcnt lgkmcnt(0)
	v_add_f32_e32 v57, v14, v15
	v_fmac_f32_e32 v34, 0xba800000, v57
	v_fmac_f32_e32 v17, 0xba800000, v57
	v_fmac_f32_e32 v35, 0xba800000, v57
	v_fmac_f32_e32 v16, 0xba800000, v57
	v_mov_b32_e32 v14, v35
	v_mov_b32_e32 v15, v17
	v_mov_b32_e32 v17, v34
	v_pk_mul_f32 v[44:45], v[14:15], v[14:15]
	v_pk_mul_f32 v[34:35], v[16:17], v[16:17]
	v_fmac_f32_e32 v36, 0xba800000, v57
	v_pk_mov_b32 v[46:47], v[34:35], v[44:45] op_sel:[1,0]
	v_mov_b32_e32 v35, v45
	v_pk_add_f32 v[34:35], v[46:47], v[34:35]
	v_fmac_f32_e32 v13, 0xba800000, v57
	v_fmac_f32_e32 v37, 0xba800000, v57
	v_pk_add_f32 v[46:47], v[34:35], v[34:35] op_sel_hi:[0,1]
	v_fmac_f32_e32 v12, 0xba800000, v57
	v_mov_b32_e32 v34, v37
	v_mov_b32_e32 v35, v13
	v_mov_b32_e32 v13, v36
	v_pk_mul_f32 v[44:45], v[34:35], v[34:35]
	v_pk_mul_f32 v[36:37], v[12:13], v[12:13]
	v_fmac_f32_e32 v8, 0xba800000, v57
	v_pk_mov_b32 v[48:49], v[36:37], v[44:45] op_sel:[1,0]
	v_mov_b32_e32 v37, v45
	v_pk_add_f32 v[36:37], v[48:49], v[36:37]
	v_fmac_f32_e32 v9, 0xba800000, v57
	v_pk_add_f32 v[36:37], v[36:37], v[36:37] op_sel_hi:[0,1]
	v_fmac_f32_e32 v10, 0xba800000, v57
	v_mul_f32_e32 v36, v8, v8
	v_fmac_f32_e32 v11, 0xba800000, v57
	v_pk_fma_f32 v[48:49], v[8:9], v[8:9], v[36:37] op_sel_hi:[1,1,0]
	v_mul_f32_e32 v36, v10, v10
	v_pk_fma_f32 v[58:59], v[10:11], v[10:11], v[36:37] op_sel_hi:[1,1,0]
	v_fmamk_f32 v5, v57, 0xba800000, v5
	v_fmac_f32_e32 v4, 0xba800000, v57
	v_mul_f32_e32 v48, v4, v4
	v_mul_f32_e32 v58, v5, v5
	v_fmamk_f32 v45, v57, 0xba800000, v7
	v_fmamk_f32 v44, v57, 0xba800000, v6
	v_pk_add_f32 v[6:7], v[48:49], v[58:59]
	v_mul_f32_e32 v46, v44, v44
	v_mul_f32_e32 v36, v45, v45
	v_pk_add_f32 v[36:37], v[46:47], v[36:37]
	v_pk_add_f32 v[6:7], v[6:7], v[36:37]
	s_nop 0
	v_add_f32_e32 v6, v6, v7
	ds_bpermute_b32 v7, v51, v6
	s_waitcnt lgkmcnt(0)
	v_add_f32_e32 v6, v6, v7
	ds_bpermute_b32 v7, v52, v6
	s_waitcnt lgkmcnt(0)
	v_add_f32_e32 v6, v6, v7
	ds_bpermute_b32 v7, v53, v6
	s_waitcnt lgkmcnt(0)
	v_add_f32_e32 v6, v6, v7
	ds_bpermute_b32 v7, v54, v6
	s_waitcnt lgkmcnt(0)
	v_add_f32_e32 v6, v6, v7
	ds_bpermute_b32 v7, v55, v6
	s_waitcnt lgkmcnt(0)
	v_add_f32_e32 v6, v6, v7
	ds_bpermute_b32 v7, v56, v6
	s_waitcnt lgkmcnt(0)
	v_add_f32_e32 v6, v6, v7
	v_fmamk_f32 v6, v6, 0x3a800000, v156
	v_cmp_gt_f32_e32 vcc, s92, v6
	v_mul_f32_e32 v7, 0x4b800000, v6
	s_nop 0
	v_cndmask_b32_e32 v6, v6, v7, vcc
	v_rsq_f32_e32 v6, v6
	s_nop 0
	v_mul_f32_e32 v7, 0x45800000, v6
	v_cndmask_b32_e32 v46, v6, v7, vcc
	v_pk_mul_f32 v[6:7], v[16:17], v[46:47] op_sel_hi:[1,0]
	v_pk_mul_f32 v[14:15], v[14:15], v[46:47] op_sel_hi:[1,0]
	v_pk_mul_f32 v[4:5], v[4:5], v[46:47] op_sel_hi:[1,0]
	v_pk_mul_f32 v[44:45], v[44:45], v[46:47] op_sel_hi:[1,0]
	v_cmp_lt_i32_e32 vcc, s94, v50
	s_or_b64 s[40:41], vcc, s[40:41]
	s_waitcnt vmcnt(0)
	v_mov_b32_e32 v48, v19
	v_pk_fma_f32 v[16:17], v[186:187], v[14:15], v[212:213]
	v_pk_fma_f32 v[14:15], v[184:185], v[6:7], v[210:211]
	v_pk_mul_f32 v[6:7], v[12:13], v[46:47] op_sel_hi:[1,0]
	v_pk_mul_f32 v[12:13], v[34:35], v[46:47] op_sel_hi:[1,0]
	v_pk_fma_f32 v[34:35], v[188:189], v[6:7], v[214:215]
	v_pk_fma_f32 v[36:37], v[190:191], v[12:13], v[216:217]
	v_pk_mul_f32 v[6:7], v[8:9], v[46:47] op_sel_hi:[1,0]
	v_pk_mul_f32 v[8:9], v[10:11], v[46:47] op_sel_hi:[1,0]
	v_mov_b32_e32 v46, v21
	v_pk_fma_f32 v[8:9], v[194:195], v[8:9], v[220:221]
	v_pk_fma_f32 v[6:7], v[192:193], v[6:7], v[218:219]
	v_pk_fma_f32 v[10:11], v[196:197], v[4:5], v[222:223]
	v_cvt_pk_bf16_f32 v4, v14, v15
	v_cvt_pk_bf16_f32 v5, v16, v17
	global_store_dwordx4 v[40:41], v[14:17], off offset:-2048
	global_store_dwordx2 v[42:43], v[4:5], off offset:-1024
	global_store_dwordx4 v[40:41], v[34:37], off offset:-1024
	v_cvt_pk_bf16_f32 v4, v34, v35
	v_cvt_pk_bf16_f32 v5, v36, v37
	v_pk_fma_f32 v[12:13], v[198:199], v[44:45], v[224:225]
	global_store_dwordx2 v[42:43], v[4:5], off offset:-512
	global_store_dwordx4 v[40:41], v[6:9], off
	v_cvt_pk_bf16_f32 v4, v6, v7
	v_cvt_pk_bf16_f32 v5, v8, v9
	global_store_dwordx2 v[42:43], v[4:5], off
	global_store_dwordx4 v[40:41], v[10:13], off offset:1024
	v_cvt_pk_bf16_f32 v4, v10, v11
	v_cvt_pk_bf16_f32 v5, v12, v13
	global_store_dwordx2 v[42:43], v[4:5], off offset:512
	v_mov_b64_e32 v[4:5], v[18:19]
	v_lshl_add_u64 v[40:41], v[40:41], 0, s[36:37]
	v_lshl_add_u64 v[42:43], v[42:43], 0, s[38:39]
	v_mov_b64_e32 v[6:7], v[20:21]
	v_mov_b32_e32 v16, v30
	v_mov_b32_e32 v34, v31
	v_mov_b32_e32 v35, v32
	v_mov_b32_e32 v17, v33
	v_mov_b32_e32 v12, v26
	v_mov_b32_e32 v36, v27
	v_mov_b32_e32 v37, v28
	v_mov_b32_e32 v13, v29
	v_mov_b32_e32 v8, v22
	v_mov_b32_e32 v9, v23
	v_mov_b32_e32 v10, v24
	v_mov_b32_e32 v11, v25
	v_mov_b32_e32 v44, v18
	v_mov_b32_e32 v14, v20
	s_andn2_b64 exec, exec, s[40:41]
	s_cbranch_execz .LBB0_682
